# differential attention: gate tile requested in the item prologue beside the first K/V tile
# baseline (speedup 1.0000x reference)
; #define LAS __attribute__((address_space(3)))
; template <int MODE>
; __device__ __forceinline__ void attn_item(LAS unsigned char* lds, const AttnArgs& a, const int tid) {
;     ...
;     bf16x8 qf[NKS];
;     { const bf16_t* qrow = a.Q + (size_t)(qw0 + r) * a.ldq + map * 64 + 8 * h;
; #pragma unroll
;       for (int ks = 0; ks < NKS; ++ks) qf[ks] = *(const bf16x8*)(qrow + 16 * ks); }
;     if (MODE == 1) {
;         LAS float* cl = (LAS float*)(lds + A_CS); LAS float* wtot = (LAS float*)(lds + A_LUT);
;         const int n = a.q0 + 256; const bool on = 8 * tid < n;
;         float v[8]; float run = 0.f;
;         const float* lp = a.c + 8 * tid;
;         f32x4 x0 = {0.f, 0.f, 0.f, 0.f}, x1 = x0; if (on) { x0 = *(const f32x4*)lp; x1 = *(const f32x4*)(lp + 4); }
; #pragma unroll
;         for (int e = 0; e < 8; ++e) { run += (e < 4) ? x0[e & 3] : x1[e & 3]; v[e] = run; }
;         float incl = run;
; #pragma unroll
;         for (int o = 1; o < 64; o <<= 1) { const float x = __shfl_up(incl, o); if (lane >= o) incl += x; }
;         if (lane == 63) wtot[wave] = incl;
;         __syncthreads();
;         float pre = incl - run;
;         for (int w = 0; w < wave; ++w) pre += wtot[w];
;         if (on) {
; #pragma unroll
;             for (int e = 0; e < 8; ++e) cl[8 * tid + e] = -(pre + v[e]) * LOG2E; }
;     }
;     unsigned kaddr[NKS];
;     { const unsigned X = ((r & 3u) << 2) | ((r >> 2) & 3u);
; #pragma unroll
;       for (int ks = 0; ks < NKS; ++ks) kaddr[ks] = 256u * r + 16u * ((unsigned)(2 * (map * 4 + ks) + h) ^ X); }
;     unsigned vaddr[4][2];
;     { const unsigned q = (lane & 15) >> 2, p = lane & 3, blk = (lane >> 4) & 1;
; #pragma unroll
;       for (int dt = 0; dt < 4; ++dt)
; #pragma unroll
;           for (int t2 = 0; t2 < 2; ++t2) vaddr[dt][t2] = 16384u + off_b(8 * t2 + 4 * h + q, 4 * dt + 2 * blk + (p >> 1)) + 8u * (p & 1); }
;     const unsigned sX = ((unsigned)(lane >> 4) << 2) | (unsigned)(wave & 3);
;     const size_t sgoff = (size_t)(4 * wave + (lane >> 4)) * a.ldkv + (size_t)(((unsigned)(lane & 15) ^ sX) * 8u);
;     const bf16_t* kg = a.K + sgoff; const bf16_t* vg = a.V + sgoff;
;     const size_t tstep = (size_t)64 * a.ldkv, hstep = (size_t)32 * a.ldkv;
;     ...
;     float l = 0.f;
;     f32x16 o[4];
; #pragma unroll
;     for (int dt = 0; dt < 4; ++dt)
; #pragma unroll
;         for (int i = 0; i < 16; ++i) o[dt][i] = 0.f;
;     AT_DMA(0, 0);
.LBB0_16:
	s_or_b64 exec, exec, s[8:9]
	s_bfe_u32 s7, s26, 0x50003
	s_and_b32 s55, s19, 7
	s_and_b32 s8, s26, 0x100
	s_xor_b32 s9, s7, 31
	s_cmp_eq_u32 s8, 0
	s_cselect_b32 s14, s7, s9
	s_ashr_i32 s7, s6, 31
	s_mul_i32 s9, s6, 0x3800000
	s_mul_hi_i32 s8, s6, 0x3800000
	s_add_u32 s36, s30, s9
	s_addc_u32 s37, s31, s8
	s_lshl_b32 s8, s11, 7
	s_ashr_i32 s9, s8, 31
	s_lshl_b64 s[8:9], s[8:9], 1
	s_add_u32 s12, s36, s8
	s_addc_u32 s13, s37, s9
	s_ashr_i32 s11, s28, 6
	s_and_b32 s34, s11, 3
	s_lshl_b32 s27, s14, 7
	s_lshl_b32 s38, s34, 5
	s_lshl_b32 s39, s14, 1
	s_or_b32 s14, s38, s27
	s_ashr_i32 s29, s28, 8
	v_or_b32_e32 v0, s14, v157
	s_lshr_b32 s43, s14, 6
	v_mul_u32_u24_e32 v0, 0x1c00, v0
	s_lshl_b32 s14, s29, 6
	v_lshl_add_u64 v[2:3], v[0:1], 1, s[12:13]
	s_ashr_i32 s15, s14, 31
	v_lshl_add_u64 v[2:3], s[14:15], 1, v[2:3]
	v_mov_b32_e32 v135, v1
	v_lshl_add_u64 v[2:3], v[2:3], 0, v[134:135]
	global_load_dwordx4 v[116:119], v[2:3], off
	global_load_dwordx4 v[120:123], v[2:3], off offset:32
	global_load_dwordx4 v[124:127], v[2:3], off offset:64
	global_load_dwordx4 v[128:131], v[2:3], off offset:96
	v_lshl_or_b32 v0, s11, 2, v161
	s_movk_i32 s14, 0x1c00
	v_bitop3_b32 v10, s34, v160, v162 bitop3:0x36
	v_mad_i64_i32 v[4:5], s[14:15], v0, s14, 0
	v_lshl_or_b32 v4, v10, 3, v4
	v_lshl_add_u64 v[4:5], v[4:5], 1, s[12:13]
	s_mov_b64 s[0:1], 0xc00
	s_lshl_b32 s11, s11, 10
	v_lshl_add_u64 v[6:7], v[4:5], 0, s[0:1]
	s_add_i32 s44, s11, 0
	s_mov_b32 m0, s44
	s_nop 0
	global_load_lds_dwordx4 v[6:7], off
	s_mov_b64 s[12:13], 0x70c00
	s_mov_b64 s[0:1], 0x1800
	v_lshl_add_u64 v[2:3], v[4:5], 0, s[12:13]
	s_add_i32 s45, s44, 0x2000
	s_mov_b32 m0, s45
	s_nop 0
	global_load_lds_dwordx4 v[2:3], off
	s_mov_b64 s[12:13], 0x71800
	v_lshl_add_u64 v[8:9], v[4:5], 0, s[0:1]
	s_add_i32 s46, s44, 0x4000
	s_mov_b32 m0, s46
	s_nop 0
	global_load_lds_dwordx4 v[8:9], off
	v_lshl_add_u64 v[2:3], v[4:5], 0, s[12:13]
	s_add_i32 s11, 0, 0x14000
	s_add_i32 s47, s44, 0x6000
	s_mov_b32 m0, s47
	s_nop 0
	global_load_lds_dwordx4 v[2:3], off
	s_add_u32 s98, s36, s18
	s_addc_u32 s99, s37, 0
	s_add_u32 s98, s98, s8
	s_addc_u32 s99, s99, s9
	v_lshlrev_b32_e32 v236, 3, v160
	v_ashrrev_i32_e32 v237, 31, v236
	v_lshl_add_u64 v[236:237], v[236:237], 1, s[98:99]
	v_add_u32_e32 v238, s27, v167
	v_mov_b32_e32 v249, 0x3800
	v_mad_i64_i32 v[240:241], vcc, v238, v249, v[236:237]
	v_add_u32_e32 v239, 32, v238
	v_mad_i64_i32 v[242:243], vcc, v239, v249, v[236:237]
	v_add_u32_e32 v239, 64, v238
	v_mad_i64_i32 v[244:245], vcc, v239, v249, v[236:237]
	v_add_u32_e32 v239, 0x60, v238
	v_mad_i64_i32 v[246:247], vcc, v239, v249, v[236:237]
	global_load_dwordx4 v[220:223], v[240:241], off offset:1024
	global_load_dwordx4 v[224:227], v[242:243], off offset:1024
	global_load_dwordx4 v[228:231], v[244:245], off offset:1024
	global_load_dwordx4 v[232:235], v[246:247], off offset:1024
	v_mov_b32_e32 v2, s11
	s_lshl_b32 s11, s29, 3
	s_waitcnt vmcnt(0)
	s_waitcnt lgkmcnt(0)
	s_barrier
	s_add_i32 s10, s10, s55
	s_add_i32 s42, s39, 2
	s_add_i32 s48, s43, -2
	s_add_i32 s49, s44, 0x8000
	s_add_i32 s50, s44, 0xa000
	s_add_i32 s51, s44, 0xc000
	s_add_i32 s54, s44, 0xe000
	v_mov_b32_e32 v14, v1
	v_mov_b32_e32 v15, v1
	v_mov_b32_e32 v4, v1
	v_mov_b32_e32 v5, v1
	v_mov_b32_e32 v6, v1
	v_mov_b32_e32 v7, v1
	v_mov_b32_e32 v8, v1
	v_mov_b32_e32 v9, v1
	v_mov_b32_e32 v11, v1
	v_mov_b32_e32 v12, v1
	v_mov_b32_e32 v13, v1
	s_mov_b32 s35, 0
	v_mov_b32_e32 v181, 0
	s_waitcnt vmcnt(0)
	ds_read_b32 v136, v2
	v_or_b32_e32 v2, s11, v158
	v_bitop3_b32 v3, v2, v163, 6 bitop3:0x36
	v_lshl_add_u32 v16, v3, 4, v164
	v_bitop3_b32 v3, v2, v163, 4 bitop3:0x36
	v_bitop3_b32 v2, v2, v163, 2 bitop3:0x36
	v_lshl_add_u32 v18, v2, 4, v164
	v_bitop3_b32 v2, s11, v163, v158 bitop3:0x36
	v_lshl_add_u32 v19, v2, 4, v164
	v_or_b32_e32 v2, s27, v157
	v_or_b32_e32 v2, s38, v2
	v_lshlrev_b32_e32 v2, 2, v2
	s_movk_i32 s11, 0x3800
	v_lshl_add_u32 v17, v3, 4, v164
	v_sub_u32_e32 v135, v168, v2
	v_mad_i64_i32 v[2:3], s[12:13], v0, s11, 0
	s_mul_i32 s11, s6, 12
	s_sub_i32 s10, s10, s11
	s_lshl_b32 s10, s10, 7
	s_ashr_i32 s11, s10, 31
	s_lshl_b64 s[10:11], s[10:11], 1
	v_mad_i64_i32 v[2:3], s[12:13], s6, v209, v[2:3]
	s_add_u32 s10, s16, s10
	v_lshl_or_b32 v2, v10, 4, v2
	s_addc_u32 s11, s17, s11
	v_lshl_add_u64 v[138:139], s[10:11], 0, v[2:3]
	v_mov_b32_e32 v0, v1
	v_mov_b32_e32 v2, v1
	v_mov_b32_e32 v3, v1
	v_mov_b32_e32 v10, v1
	v_add_u32_e32 v184, 0, v19
	v_add_u32_e32 v185, 0, v18
	v_add_u32_e32 v186, 0, v17
	v_add_u32_e32 v187, 0, v16
	v_mov_b64_e32 v[30:31], v[14:15]
	v_mov_b64_e32 v[46:47], v[14:15]
	v_mov_b64_e32 v[62:63], v[14:15]
	v_mov_b64_e32 v[78:79], v[14:15]
	s_waitcnt lgkmcnt(0)
	v_mov_b32_e32 v137, v136
	v_mov_b64_e32 v[28:29], v[12:13]
	v_mov_b64_e32 v[26:27], v[10:11]
	v_mov_b64_e32 v[24:25], v[8:9]
	v_mov_b64_e32 v[22:23], v[6:7]
	v_mov_b64_e32 v[20:21], v[4:5]
	v_mov_b64_e32 v[18:19], v[2:3]
	v_mov_b64_e32 v[16:17], v[0:1]
	v_mov_b64_e32 v[44:45], v[12:13]
	v_mov_b64_e32 v[42:43], v[10:11]
	v_mov_b64_e32 v[40:41], v[8:9]
	v_mov_b64_e32 v[38:39], v[6:7]
	v_mov_b64_e32 v[36:37], v[4:5]
	v_mov_b64_e32 v[34:35], v[2:3]
	v_mov_b64_e32 v[32:33], v[0:1]
	v_mov_b64_e32 v[60:61], v[12:13]
	v_mov_b64_e32 v[58:59], v[10:11]
	v_mov_b64_e32 v[56:57], v[8:9]
	v_mov_b64_e32 v[54:55], v[6:7]
	v_mov_b64_e32 v[52:53], v[4:5]
	v_mov_b64_e32 v[50:51], v[2:3]
	v_mov_b64_e32 v[48:49], v[0:1]
	v_mov_b64_e32 v[76:77], v[12:13]
	v_mov_b64_e32 v[74:75], v[10:11]
	v_mov_b64_e32 v[72:73], v[8:9]
	v_mov_b64_e32 v[70:71], v[6:7]
	v_mov_b64_e32 v[68:69], v[4:5]
	v_mov_b64_e32 v[66:67], v[2:3]
	v_mov_b64_e32 v[64:65], v[0:1]
	s_branch .LBB0_19

; #define LAS __attribute__((address_space(3)))
; template <int MODE>
; __device__ __forceinline__ void attn_item(LAS unsigned char* lds, const AttnArgs& a, const int tid) {
;     ...
;     l += __shfl_xor(l, 32);
;     const float inv = 1.f / l;
;     ...
;         LAS float* xb = (LAS float*)(lds + (wave & 3) * 16384);
;         int ch = tid & 15, r0 = tid >> 4, lrow = 32 * (wave & 3) + r, hh = h;
;         asm volatile("" : "+v"(ch), "+v"(r0), "+v"(lrow), "+v"(hh));
;         { u32x4 gv[4];
; #pragma unroll
;           for (int i = 0; i < 4; ++i) gv[i] = *(const u32x4*)(a.G + (size_t)(a.q0 + r0 + 32 * i) * a.ldg + 8 * ch);
; #pragma unroll
;           for (int i = 0; i < 4; ++i) *(LAS u32x4*)(lds + 98304 + off_b(r0 + 32 * i, ch)) = gv[i]; }
;         if (map == 1) {
;             const float f = inv * a.lam;
; #pragma unroll
;             for (int dt = 0; dt < 4; ++dt)
; #pragma unroll
;                 for (int i = 0; i < 16; ++i) xb[(dt * 16 + i) * 64 + lane] = o[dt][i] * f;
.LBB0_42:
	s_add_u32 s10, s36, s18
	s_addc_u32 s11, s37, 0
	v_or_b32_e32 v3, s38, v157
	v_mov_b32_e32 v0, v160
	v_mov_b32_e32 v135, v167
	v_mov_b32_e32 v2, v158
	s_add_u32 s10, s10, s8
	s_addc_u32 s11, s11, s9
	v_lshlrev_b32_e32 v14, 3, v0
	v_add_u32_e32 v80, s27, v135
	v_ashrrev_i32_e32 v15, 31, v14
	v_lshl_add_u64 v[12:13], v[14:15], 1, s[10:11]
	s_movk_i32 s12, 0x3800
	v_add_u32_e32 v6, 32, v80
	v_add_u32_e32 v81, 64, v80
	v_mad_i64_i32 v[4:5], s[10:11], v80, s12, v[12:13]
	v_mad_i64_i32 v[8:9], s[10:11], v6, s12, v[12:13]
	v_mad_i64_i32 v[82:83], s[10:11], v81, s12, v[12:13]
	v_add_u32_e32 v81, 0x60, v80
	s_nop 0
	v_mad_i64_i32 v[12:13], s[10:11], v81, s12, v[12:13]
	s_nop 0
	v_and_b32_e32 v13, 64, v204
	v_xor_b32_e32 v12, 32, v204
	v_add_u32_e32 v13, 64, v13
	v_cmp_lt_i32_e32 vcc, v12, v13
	v_lshlrev_b32_e32 v81, 2, v135
	v_bfe_u32 v90, v135, 2, 2
	v_cndmask_b32_e32 v12, v204, v12, vcc
	v_lshlrev_b32_e32 v187, 2, v12
	v_and_b32_e32 v12, 12, v81
	ds_bpermute_b32 v81, v187, v181
	v_bitop3_b32 v0, v12, v0, v90 bitop3:0x36
	s_lshl_b32 s10, s34, 14
	v_lshl_add_u32 v184, v0, 4, s91
	s_add_i32 s12, s10, 0
	s_waitcnt lgkmcnt(0)
	v_add_f32_e32 v0, v181, v81
	v_div_scale_f32 v12, s[10:11], v0, v0, 1.0
	v_rcp_f32_e32 v81, v12
	v_lshlrev_b32_e32 v13, 8, v135
	v_add_u32_e32 v181, v184, v13
	v_div_scale_f32 v13, vcc, 1.0, v0, 1.0
	v_fma_f32 v90, -v12, v81, 1.0
	v_fmac_f32_e32 v81, v90, v81
	v_mul_f32_e32 v90, v13, v81
	v_fma_f32 v91, -v12, v90, v13
	v_fmac_f32_e32 v90, v91, v81
	v_fma_f32 v12, -v12, v90, v13
	v_div_fmas_f32 v12, v12, v81, v90
	s_cmp_eq_u32 s29, 1
	v_div_fixup_f32 v0, v12, v0, 1.0
	s_waitcnt vmcnt(0)
	ds_write_b128 v181, v[220:223]
	ds_write_b128 v181, v[224:227] offset:8192
	ds_write_b128 v181, v[228:231] offset:16384
	ds_write_b128 v181, v[232:235] offset:24576
	v_lshl_add_u32 v4, v182, 2, s12
	s_cbranch_scc0 .LBB0_44
	v_mul_f32_e32 v5, v154, v0
	v_mul_f32_e32 v6, v64, v5
	v_mul_f32_e32 v7, v65, v5
	ds_write2st64_b32 v4, v6, v7 offset1:1
	v_mul_f32_e32 v6, v66, v5
	v_mul_f32_e32 v7, v67, v5
	ds_write2st64_b32 v4, v6, v7 offset0:2 offset1:3
	v_mul_f32_e32 v6, v68, v5
	v_mul_f32_e32 v7, v69, v5
	ds_write2st64_b32 v4, v6, v7 offset0:4 offset1:5
	v_mul_f32_e32 v6, v70, v5
	v_mul_f32_e32 v7, v71, v5
	ds_write2st64_b32 v4, v6, v7 offset0:6 offset1:7
	v_mul_f32_e32 v6, v72, v5
	v_mul_f32_e32 v7, v73, v5
	ds_write2st64_b32 v4, v6, v7 offset0:8 offset1:9
	v_mul_f32_e32 v6, v74, v5
	v_mul_f32_e32 v7, v75, v5
	ds_write2st64_b32 v4, v6, v7 offset0:10 offset1:11
	v_mul_f32_e32 v6, v76, v5
	v_mul_f32_e32 v7, v77, v5
	ds_write2st64_b32 v4, v6, v7 offset0:12 offset1:13
	v_mul_f32_e32 v6, v78, v5
	v_mul_f32_e32 v7, v79, v5
	ds_write2st64_b32 v4, v6, v7 offset0:14 offset1:15
	v_mul_f32_e32 v6, v48, v5
	v_mul_f32_e32 v7, v49, v5
	ds_write2st64_b32 v4, v6, v7 offset0:16 offset1:17
	v_mul_f32_e32 v6, v50, v5
	v_mul_f32_e32 v7, v51, v5
	ds_write2st64_b32 v4, v6, v7 offset0:18 offset1:19
	v_mul_f32_e32 v6, v52, v5
	v_mul_f32_e32 v7, v53, v5
	ds_write2st64_b32 v4, v6, v7 offset0:20 offset1:21
	v_mul_f32_e32 v6, v54, v5
	v_mul_f32_e32 v7, v55, v5
	ds_write2st64_b32 v4, v6, v7 offset0:22 offset1:23
	v_mul_f32_e32 v6, v56, v5
	v_mul_f32_e32 v7, v57, v5
	ds_write2st64_b32 v4, v6, v7 offset0:24 offset1:25
	v_mul_f32_e32 v6, v58, v5
	v_mul_f32_e32 v7, v59, v5
	ds_write2st64_b32 v4, v6, v7 offset0:26 offset1:27
	v_mul_f32_e32 v6, v60, v5
	v_mul_f32_e32 v7, v61, v5
	ds_write2st64_b32 v4, v6, v7 offset0:28 offset1:29
	v_mul_f32_e32 v6, v62, v5
	v_mul_f32_e32 v7, v63, v5
	ds_write2st64_b32 v4, v6, v7 offset0:30 offset1:31
	v_mul_f32_e32 v6, v32, v5
	v_mul_f32_e32 v7, v33, v5
	ds_write2st64_b32 v4, v6, v7 offset0:32 offset1:33
	v_mul_f32_e32 v6, v34, v5
	v_mul_f32_e32 v7, v35, v5
	ds_write2st64_b32 v4, v6, v7 offset0:34 offset1:35
	v_mul_f32_e32 v6, v36, v5
	v_mul_f32_e32 v7, v37, v5
	ds_write2st64_b32 v4, v6, v7 offset0:36 offset1:37
	v_mul_f32_e32 v6, v38, v5
	v_mul_f32_e32 v7, v39, v5
	ds_write2st64_b32 v4, v6, v7 offset0:38 offset1:39
	v_mul_f32_e32 v6, v40, v5
	v_mul_f32_e32 v7, v41, v5
	ds_write2st64_b32 v4, v6, v7 offset0:40 offset1:41
	v_mul_f32_e32 v6, v42, v5
	v_mul_f32_e32 v7, v43, v5
	ds_write2st64_b32 v4, v6, v7 offset0:42 offset1:43
	v_mul_f32_e32 v6, v44, v5
	v_mul_f32_e32 v7, v45, v5
	ds_write2st64_b32 v4, v6, v7 offset0:44 offset1:45
	v_mul_f32_e32 v6, v46, v5
	v_mul_f32_e32 v7, v47, v5
	ds_write2st64_b32 v4, v6, v7 offset0:46 offset1:47
	v_mul_f32_e32 v6, v16, v5
	v_mul_f32_e32 v7, v17, v5
	ds_write2st64_b32 v4, v6, v7 offset0:48 offset1:49
	v_mul_f32_e32 v6, v18, v5
	v_mul_f32_e32 v7, v19, v5
	ds_write2st64_b32 v4, v6, v7 offset0:50 offset1:51
	v_mul_f32_e32 v6, v20, v5
	v_mul_f32_e32 v7, v21, v5
	ds_write2st64_b32 v4, v6, v7 offset0:52 offset1:53
	v_mul_f32_e32 v6, v22, v5
	v_mul_f32_e32 v7, v23, v5
	ds_write2st64_b32 v4, v6, v7 offset0:54 offset1:55
	v_mul_f32_e32 v6, v24, v5
	v_mul_f32_e32 v7, v25, v5
	ds_write2st64_b32 v4, v6, v7 offset0:56 offset1:57
	v_mul_f32_e32 v6, v26, v5
	v_mul_f32_e32 v7, v27, v5
	ds_write2st64_b32 v4, v6, v7 offset0:58 offset1:59
	v_mul_f32_e32 v6, v28, v5
	v_mul_f32_e32 v7, v29, v5
	ds_write2st64_b32 v4, v6, v7 offset0:60 offset1:61
	v_mul_f32_e32 v6, v30, v5
	v_mul_f32_e32 v5, v31, v5
	ds_write2st64_b32 v4, v6, v5 offset0:62 offset1:63
